# plus grid barrier: last arriver bumps every XCD generation word directly
# speedup vs baseline: 1.0303x; 1.0055x over previous
.LBB0_553:
	s_or_b64 exec, exec, s[2:3]
	s_and_saveexec_b64 s[2:3], s[20:21]
	s_cbranch_execz .LBB0_555
	global_atomic_add v[2:3], v243, off
	v_readlane_b32 s22, v253, 21
	s_nop 3
	v_cmp_eq_u32_e32 vcc, s22, v2
	s_and_saveexec_b64 s[22:23], vcc
	s_cbranch_execz .Lxg_skip
	s_add_u32 s28, s62, 0xfa92400
	s_addc_u32 s29, s63, 0
	global_atomic_add v1, v243, s[28:29]
	global_atomic_add v1, v243, s[28:29] offset:256
	global_atomic_add v1, v243, s[28:29] offset:512
	global_atomic_add v1, v243, s[28:29] offset:768
	global_atomic_add v1, v243, s[28:29] offset:1024
	global_atomic_add v1, v243, s[28:29] offset:1280
	global_atomic_add v1, v243, s[28:29] offset:1536
	global_atomic_add v1, v243, s[28:29] offset:1792
	global_atomic_add v1, v243, s[28:29] offset:2048
	global_atomic_add v1, v243, s[28:29] offset:2304
	global_atomic_add v1, v243, s[28:29] offset:2560
	global_atomic_add v1, v243, s[28:29] offset:2816
	global_atomic_add v1, v243, s[28:29] offset:3072
	global_atomic_add v1, v243, s[28:29] offset:3328
	global_atomic_add v1, v243, s[28:29] offset:3584
	global_atomic_add v1, v243, s[28:29] offset:3840

.LBB0_555:
	s_or_b64 exec, exec, s[2:3]
	s_mov_b64 s[2:3], exec
	v_mbcnt_lo_u32_b32 v0, s2, 0
	v_mbcnt_hi_u32_b32 v0, s3, v0
	v_cmp_eq_u32_e32 vcc, 0, v0
	s_waitcnt vmcnt(0)
	buffer_inv sc1
	s_and_saveexec_b64 s[20:21], vcc
	s_cbranch_execz .LBB0_557
	s_bcnt1_i32_b64 s2, s[2:3]
	v_mov_b32_e32 v0, s2
	v_readlane_b32 s2, v253, 17
	v_readlane_b32 s3, v253, 18
	s_nop 4
	s_nop 0
